# v38: P4 last round as 180 half units + two weight-conversion items in flight per wave, non-temporal conversion traffic
# speedup vs baseline: 1.0129x; 1.0129x over previous
.LBB0_774:
	s_abs_i32 s0, s33
	v_cvt_f32_u32_e32 v2, s0
	s_sub_i32 s1, 0, s0
	v_rcp_iflag_f32_e32 v2, v2
	s_nop 0
	v_mul_f32_e32 v2, 0x4f7ffffe, v2
	v_cvt_u32_f32_e32 v2, v2
	s_nop 0
	v_readfirstlane_b32 s2, v2
	s_mul_i32 s1, s1, s2
	s_mul_hi_u32 s1, s2, s1
	s_add_i32 s2, s2, s1
	s_mul_hi_u32 s1, s2, 0x35a
	s_mul_i32 s1, s1, s0
	s_sub_i32 s1, 0x35a, s1
	s_sub_i32 s2, s1, s0
	s_cmp_ge_u32 s1, s0
	s_cselect_b32 s1, s2, s1
	s_sub_i32 s2, s1, s0
	s_cmp_ge_u32 s1, s0
	s_cselect_b32 s0, s2, s1
	s_movk_i32 s0, 180
	s_cmp_ge_i32 s24, s0
	s_cbranch_scc0 .LBB0_796
	s_sub_i32 s1, s24, s0
	s_lshl_b32 s1, s1, 3
	s_add_i32 s6, s1, s83
	s_cmpk_gt_u32 s6, 0x127f
	s_cbranch_scc1 .LBB0_796
	s_sub_i32 s7, s33, s0
	s_lshl_b32 s7, s7, 3
	v_mbcnt_lo_u32_b32 v1, -1, 0
	v_mbcnt_hi_u32_b32 v1, -1, v1
	v_and_b32_e32 v2, 31, v1
	v_lshrrev_b32_e32 v3, 5, v1
	s_mul_i32 s4, s83, 0x4400
	v_mad_u32_u24 v4, v3, 33, v2
	v_lshl_add_u32 v4, v4, 2, s4
	v_and_b32_e32 v5, 7, v1
	v_lshrrev_b32_e32 v6, 3, v1
	v_mul_u32_u24_e32 v7, 0x108, v5
	v_add_u32_e32 v7, v7, v6
	v_lshl_add_u32 v7, v7, 2, s4
.Lcv3_item:
	s_add_i32 s23, s6, s7
	s_cmpk_lt_u32 s23, 4736
	s_cbranch_scc0 .Lcv3_single
	s_cmpk_lt_u32 s6, 2816
	s_cbranch_scc0 .Lcv3_fo_a
	s_mul_i32 s1, s6, 5958
	s_lshr_b32 s1, s1, 20
	s_mul_i32 s2, s1, 176
	s_sub_i32 s2, s6, s2
	s_lshl_b32 s18, s2, 5
	s_lshl_b32 s17, s1, 6
	s_cmpk_lt_u32 s18, 2816
	s_cselect_b32 s2, 0, 2816
	s_cselect_b32 s3, 0, 128
	s_sub_i32 s2, s18, s2
	s_lshr_b32 s16, s2, 7
	s_lshl_b32 s16, s16, 8
	s_and_b32 s2, s2, 127
	s_add_i32 s16, s16, s2
	s_add_i32 s16, s16, s3
	s_mov_b64 s[10:11], s[40:41]
	s_movk_i32 s12, 5632
	s_movk_i32 s13, 1024
	s_add_u32 s14, s26, 0x1400000
	s_addc_u32 s15, s27, 0
	s_branch .Lcv3_go_a

.Lcv3_go_a:
	s_mul_i32 s1, s17, s12
	s_add_i32 s1, s1, s18
	s_lshl_b32 s1, s1, 2
	s_add_u32 s10, s10, s1
	s_addc_u32 s11, s11, 0
	v_mul_lo_u32 v8, v3, s12
	v_add_lshl_u32 v8, v8, v2, 2
	s_lshl_b32 s19, s12, 3
	global_load_dword v16, v8, s[10:11] nt
	s_add_u32 s10, s10, s19
	s_addc_u32 s11, s11, 0
	global_load_dword v17, v8, s[10:11] nt
	s_add_u32 s10, s10, s19
	s_addc_u32 s11, s11, 0
	global_load_dword v18, v8, s[10:11] nt
	s_add_u32 s10, s10, s19
	s_addc_u32 s11, s11, 0
	global_load_dword v19, v8, s[10:11] nt
	s_add_u32 s10, s10, s19
	s_addc_u32 s11, s11, 0
	global_load_dword v20, v8, s[10:11] nt
	s_add_u32 s10, s10, s19
	s_addc_u32 s11, s11, 0
	global_load_dword v21, v8, s[10:11] nt
	s_add_u32 s10, s10, s19
	s_addc_u32 s11, s11, 0
	global_load_dword v22, v8, s[10:11] nt
	s_add_u32 s10, s10, s19
	s_addc_u32 s11, s11, 0
	global_load_dword v23, v8, s[10:11] nt
	s_add_u32 s10, s10, s19
	s_addc_u32 s11, s11, 0
	global_load_dword v24, v8, s[10:11] nt
	s_add_u32 s10, s10, s19
	s_addc_u32 s11, s11, 0
	global_load_dword v25, v8, s[10:11] nt
	s_add_u32 s10, s10, s19
	s_addc_u32 s11, s11, 0
	global_load_dword v26, v8, s[10:11] nt
	s_add_u32 s10, s10, s19
	s_addc_u32 s11, s11, 0
	global_load_dword v27, v8, s[10:11] nt
	s_add_u32 s10, s10, s19
	s_addc_u32 s11, s11, 0
	global_load_dword v28, v8, s[10:11] nt
	s_add_u32 s10, s10, s19
	s_addc_u32 s11, s11, 0
	global_load_dword v29, v8, s[10:11] nt
	s_add_u32 s10, s10, s19
	s_addc_u32 s11, s11, 0
	global_load_dword v30, v8, s[10:11] nt
	s_add_u32 s10, s10, s19
	s_addc_u32 s11, s11, 0
	global_load_dword v31, v8, s[10:11] nt
	s_add_u32 s10, s10, s19
	s_addc_u32 s11, s11, 0
	global_load_dword v32, v8, s[10:11] nt
	s_add_u32 s10, s10, s19
	s_addc_u32 s11, s11, 0
	global_load_dword v33, v8, s[10:11] nt
	s_add_u32 s10, s10, s19
	s_addc_u32 s11, s11, 0
	global_load_dword v34, v8, s[10:11] nt
	s_add_u32 s10, s10, s19
	s_addc_u32 s11, s11, 0
	global_load_dword v35, v8, s[10:11] nt
	s_add_u32 s10, s10, s19
	s_addc_u32 s11, s11, 0
	global_load_dword v36, v8, s[10:11] nt
	s_add_u32 s10, s10, s19
	s_addc_u32 s11, s11, 0
	global_load_dword v37, v8, s[10:11] nt
	s_add_u32 s10, s10, s19
	s_addc_u32 s11, s11, 0
	global_load_dword v38, v8, s[10:11] nt
	s_add_u32 s10, s10, s19
	s_addc_u32 s11, s11, 0
	global_load_dword v39, v8, s[10:11] nt
	s_add_u32 s10, s10, s19
	s_addc_u32 s11, s11, 0
	global_load_dword v40, v8, s[10:11] nt
	s_add_u32 s10, s10, s19
	s_addc_u32 s11, s11, 0
	global_load_dword v41, v8, s[10:11] nt
	s_add_u32 s10, s10, s19
	s_addc_u32 s11, s11, 0
	global_load_dword v42, v8, s[10:11] nt
	s_add_u32 s10, s10, s19
	s_addc_u32 s11, s11, 0
	global_load_dword v43, v8, s[10:11] nt
	s_add_u32 s10, s10, s19
	s_addc_u32 s11, s11, 0
	global_load_dword v44, v8, s[10:11] nt
	s_add_u32 s10, s10, s19
	s_addc_u32 s11, s11, 0
	global_load_dword v45, v8, s[10:11] nt
	s_add_u32 s10, s10, s19
	s_addc_u32 s11, s11, 0
	global_load_dword v46, v8, s[10:11] nt
	s_add_u32 s10, s10, s19
	s_addc_u32 s11, s11, 0
	global_load_dword v47, v8, s[10:11] nt
	s_mul_i32 s1, s16, s13
	s_add_i32 s1, s1, s17
	s_lshl_b32 s1, s1, 1
	s_add_u32 s14, s14, s1
	s_addc_u32 s15, s15, 0
	s_mov_b64 s[20:21], s[14:15]
	s_mov_b32 s22, s13
	s_cmpk_lt_u32 s23, 2816
	s_cbranch_scc0 .Lcv3_fo_b
	s_mul_i32 s1, s23, 5958
	s_lshr_b32 s1, s1, 20
	s_mul_i32 s2, s1, 176
	s_sub_i32 s2, s23, s2
	s_lshl_b32 s18, s2, 5
	s_lshl_b32 s17, s1, 6
	s_cmpk_lt_u32 s18, 2816
	s_cselect_b32 s2, 0, 2816
	s_cselect_b32 s3, 0, 128
	s_sub_i32 s2, s18, s2
	s_lshr_b32 s16, s2, 7
	s_lshl_b32 s16, s16, 8
	s_and_b32 s2, s2, 127
	s_add_i32 s16, s16, s2
	s_add_i32 s16, s16, s3
	s_mov_b64 s[10:11], s[40:41]
	s_movk_i32 s12, 5632
	s_movk_i32 s13, 1024
	s_add_u32 s14, s26, 0x1400000
	s_addc_u32 s15, s27, 0
	s_branch .Lcv3_go_b
.Lcv3_fo_b:
	s_cmpk_lt_u32 s23, 4224
	s_cbranch_scc0 .Lcv3_wo_b
	s_sub_i32 s1, s23, 2816
	s_lshr_b32 s2, s1, 5
	s_and_b32 s1, s1, 31
	s_lshl_b32 s18, s1, 5
	s_lshl_b32 s17, s2, 6
	s_mov_b32 s16, s18
	s_mov_b64 s[10:11], s[42:43]
	s_movk_i32 s12, 1024
	s_movk_i32 s13, 2816
	s_add_u32 s14, s26, 0x2000000
	s_addc_u32 s15, s27, 0
	s_branch .Lcv3_go_b
.Lcv3_wo_b:
	s_sub_i32 s1, s23, 4224
	s_lshr_b32 s2, s1, 5
	s_and_b32 s1, s1, 31
	s_lshl_b32 s18, s1, 5
	s_lshl_b32 s17, s2, 6
	s_mov_b32 s16, s18
	s_mov_b64 s[10:11], s[46:47]
	s_movk_i32 s12, 1024
	s_movk_i32 s13, 1024
	s_add_u32 s14, s26, 0x2d00000
	s_addc_u32 s15, s27, 0
.Lcv3_go_b:
	s_mul_i32 s1, s17, s12
	s_add_i32 s1, s1, s18
	s_lshl_b32 s1, s1, 2
	s_add_u32 s10, s10, s1
	s_addc_u32 s11, s11, 0
	v_mul_lo_u32 v8, v3, s12
	v_add_lshl_u32 v8, v8, v2, 2
	s_lshl_b32 s19, s12, 3
	global_load_dword v48, v8, s[10:11] nt
	s_add_u32 s10, s10, s19
	s_addc_u32 s11, s11, 0
	global_load_dword v49, v8, s[10:11] nt
	s_add_u32 s10, s10, s19
	s_addc_u32 s11, s11, 0
	global_load_dword v50, v8, s[10:11] nt
	s_add_u32 s10, s10, s19
	s_addc_u32 s11, s11, 0
	global_load_dword v51, v8, s[10:11] nt
	s_add_u32 s10, s10, s19
	s_addc_u32 s11, s11, 0
	global_load_dword v52, v8, s[10:11] nt
	s_add_u32 s10, s10, s19
	s_addc_u32 s11, s11, 0
	global_load_dword v53, v8, s[10:11] nt
	s_add_u32 s10, s10, s19
	s_addc_u32 s11, s11, 0
	global_load_dword v54, v8, s[10:11] nt
	s_add_u32 s10, s10, s19
	s_addc_u32 s11, s11, 0
	global_load_dword v55, v8, s[10:11] nt
	s_add_u32 s10, s10, s19
	s_addc_u32 s11, s11, 0
	global_load_dword v56, v8, s[10:11] nt
	s_add_u32 s10, s10, s19
	s_addc_u32 s11, s11, 0
	global_load_dword v57, v8, s[10:11] nt
	s_add_u32 s10, s10, s19
	s_addc_u32 s11, s11, 0
	global_load_dword v58, v8, s[10:11] nt
	s_add_u32 s10, s10, s19
	s_addc_u32 s11, s11, 0
	global_load_dword v59, v8, s[10:11] nt
	s_add_u32 s10, s10, s19
	s_addc_u32 s11, s11, 0
	global_load_dword v60, v8, s[10:11] nt
	s_add_u32 s10, s10, s19
	s_addc_u32 s11, s11, 0
	global_load_dword v61, v8, s[10:11] nt
	s_add_u32 s10, s10, s19
	s_addc_u32 s11, s11, 0
	global_load_dword v62, v8, s[10:11] nt
	s_add_u32 s10, s10, s19
	s_addc_u32 s11, s11, 0
	global_load_dword v63, v8, s[10:11] nt
	s_add_u32 s10, s10, s19
	s_addc_u32 s11, s11, 0
	global_load_dword v64, v8, s[10:11] nt
	s_add_u32 s10, s10, s19
	s_addc_u32 s11, s11, 0
	global_load_dword v65, v8, s[10:11] nt
	s_add_u32 s10, s10, s19
	s_addc_u32 s11, s11, 0
	global_load_dword v66, v8, s[10:11] nt
	s_add_u32 s10, s10, s19
	s_addc_u32 s11, s11, 0
	global_load_dword v67, v8, s[10:11] nt
	s_add_u32 s10, s10, s19
	s_addc_u32 s11, s11, 0
	global_load_dword v68, v8, s[10:11] nt
	s_add_u32 s10, s10, s19
	s_addc_u32 s11, s11, 0
	global_load_dword v69, v8, s[10:11] nt
	s_add_u32 s10, s10, s19
	s_addc_u32 s11, s11, 0
	global_load_dword v70, v8, s[10:11] nt
	s_add_u32 s10, s10, s19
	s_addc_u32 s11, s11, 0
	global_load_dword v71, v8, s[10:11] nt
	s_add_u32 s10, s10, s19
	s_addc_u32 s11, s11, 0
	global_load_dword v72, v8, s[10:11] nt
	s_add_u32 s10, s10, s19
	s_addc_u32 s11, s11, 0
	global_load_dword v73, v8, s[10:11] nt
	s_add_u32 s10, s10, s19
	s_addc_u32 s11, s11, 0
	global_load_dword v74, v8, s[10:11] nt
	s_add_u32 s10, s10, s19
	s_addc_u32 s11, s11, 0
	global_load_dword v75, v8, s[10:11] nt
	s_add_u32 s10, s10, s19
	s_addc_u32 s11, s11, 0
	global_load_dword v76, v8, s[10:11] nt
	s_add_u32 s10, s10, s19
	s_addc_u32 s11, s11, 0
	global_load_dword v77, v8, s[10:11] nt
	s_add_u32 s10, s10, s19
	s_addc_u32 s11, s11, 0
	global_load_dword v78, v8, s[10:11] nt
	s_add_u32 s10, s10, s19
	s_addc_u32 s11, s11, 0
	global_load_dword v79, v8, s[10:11] nt
	s_mul_i32 s1, s16, s13
	s_add_i32 s1, s1, s17
	s_lshl_b32 s1, s1, 1
	s_add_u32 s14, s14, s1
	s_addc_u32 s15, s15, 0
	s_waitcnt vmcnt(63)
	ds_write_b32 v4, v16 offset:0
	s_waitcnt vmcnt(62)
	ds_write_b32 v4, v17 offset:264
	s_waitcnt vmcnt(61)
	ds_write_b32 v4, v18 offset:528
	s_waitcnt vmcnt(60)
	ds_write_b32 v4, v19 offset:792
	s_waitcnt vmcnt(59)
	ds_write_b32 v4, v20 offset:1056
	s_waitcnt vmcnt(58)
	ds_write_b32 v4, v21 offset:1320
	s_waitcnt vmcnt(57)
	ds_write_b32 v4, v22 offset:1584
	s_waitcnt vmcnt(56)
	ds_write_b32 v4, v23 offset:1848
	s_waitcnt vmcnt(55)
	ds_write_b32 v4, v24 offset:2112
	s_waitcnt vmcnt(54)
	ds_write_b32 v4, v25 offset:2376
	s_waitcnt vmcnt(53)
	ds_write_b32 v4, v26 offset:2640
	s_waitcnt vmcnt(52)
	ds_write_b32 v4, v27 offset:2904
	s_waitcnt vmcnt(51)
	ds_write_b32 v4, v28 offset:3168
	s_waitcnt vmcnt(50)
	ds_write_b32 v4, v29 offset:3432
	s_waitcnt vmcnt(49)
	ds_write_b32 v4, v30 offset:3696
	s_waitcnt vmcnt(48)
	ds_write_b32 v4, v31 offset:3960
	s_waitcnt vmcnt(47)
	ds_write_b32 v4, v32 offset:4224
	s_waitcnt vmcnt(46)
	ds_write_b32 v4, v33 offset:4488
	s_waitcnt vmcnt(45)
	ds_write_b32 v4, v34 offset:4752
	s_waitcnt vmcnt(44)
	ds_write_b32 v4, v35 offset:5016
	s_waitcnt vmcnt(43)
	ds_write_b32 v4, v36 offset:5280
	s_waitcnt vmcnt(42)
	ds_write_b32 v4, v37 offset:5544
	s_waitcnt vmcnt(41)
	ds_write_b32 v4, v38 offset:5808
	s_waitcnt vmcnt(40)
	ds_write_b32 v4, v39 offset:6072
	s_waitcnt vmcnt(39)
	ds_write_b32 v4, v40 offset:6336
	s_waitcnt vmcnt(38)
	ds_write_b32 v4, v41 offset:6600
	s_waitcnt vmcnt(37)
	ds_write_b32 v4, v42 offset:6864
	s_waitcnt vmcnt(36)
	ds_write_b32 v4, v43 offset:7128
	s_waitcnt vmcnt(35)
	ds_write_b32 v4, v44 offset:7392
	s_waitcnt vmcnt(34)
	ds_write_b32 v4, v45 offset:7656
	s_waitcnt vmcnt(33)
	ds_write_b32 v4, v46 offset:7920
	s_waitcnt vmcnt(32)
	ds_write_b32 v4, v47 offset:8184
	s_waitcnt vmcnt(31)
	ds_write_b32 v4, v48 offset:8448
	s_waitcnt vmcnt(30)
	ds_write_b32 v4, v49 offset:8712
	s_waitcnt vmcnt(29)
	ds_write_b32 v4, v50 offset:8976
	s_waitcnt vmcnt(28)
	ds_write_b32 v4, v51 offset:9240
	s_waitcnt vmcnt(27)
	ds_write_b32 v4, v52 offset:9504
	s_waitcnt vmcnt(26)
	ds_write_b32 v4, v53 offset:9768
	s_waitcnt vmcnt(25)
	ds_write_b32 v4, v54 offset:10032
	s_waitcnt vmcnt(24)
	ds_write_b32 v4, v55 offset:10296
	s_waitcnt vmcnt(23)
	ds_write_b32 v4, v56 offset:10560
	s_waitcnt vmcnt(22)
	ds_write_b32 v4, v57 offset:10824
	s_waitcnt vmcnt(21)
	ds_write_b32 v4, v58 offset:11088
	s_waitcnt vmcnt(20)
	ds_write_b32 v4, v59 offset:11352
	s_waitcnt vmcnt(19)
	ds_write_b32 v4, v60 offset:11616
	s_waitcnt vmcnt(18)
	ds_write_b32 v4, v61 offset:11880
	s_waitcnt vmcnt(17)
	ds_write_b32 v4, v62 offset:12144
	s_waitcnt vmcnt(16)
	ds_write_b32 v4, v63 offset:12408
	s_waitcnt vmcnt(15)
	ds_write_b32 v4, v64 offset:12672
	s_waitcnt vmcnt(14)
	ds_write_b32 v4, v65 offset:12936
	s_waitcnt vmcnt(13)
	ds_write_b32 v4, v66 offset:13200
	s_waitcnt vmcnt(12)
	ds_write_b32 v4, v67 offset:13464
	s_waitcnt vmcnt(11)
	ds_write_b32 v4, v68 offset:13728
	s_waitcnt vmcnt(10)
	ds_write_b32 v4, v69 offset:13992
	s_waitcnt vmcnt(9)
	ds_write_b32 v4, v70 offset:14256
	s_waitcnt vmcnt(8)
	ds_write_b32 v4, v71 offset:14520
	s_waitcnt vmcnt(7)
	ds_write_b32 v4, v72 offset:14784
	s_waitcnt vmcnt(6)
	ds_write_b32 v4, v73 offset:15048
	s_waitcnt vmcnt(5)
	ds_write_b32 v4, v74 offset:15312
	s_waitcnt vmcnt(4)
	ds_write_b32 v4, v75 offset:15576
	s_waitcnt vmcnt(3)
	ds_write_b32 v4, v76 offset:15840
	s_waitcnt vmcnt(2)
	ds_write_b32 v4, v77 offset:16104
	s_waitcnt vmcnt(1)
	ds_write_b32 v4, v78 offset:16368
	s_waitcnt vmcnt(0)
	ds_write_b32 v4, v79 offset:16632
	s_waitcnt lgkmcnt(0)
	v_mul_lo_u32 v9, v6, s22
	v_lshl_add_u32 v96, v5, 3, v9
	v_lshlrev_b32_e32 v9, 1, v96
	s_lshl_b32 s19, s22, 4
	ds_read_b32 v112, v7 offset:0
	ds_read_b32 v113, v7 offset:132
	ds_read_b32 v114, v7 offset:264
	ds_read_b32 v115, v7 offset:396
	ds_read_b32 v116, v7 offset:528
	ds_read_b32 v117, v7 offset:660
	ds_read_b32 v118, v7 offset:792
	ds_read_b32 v119, v7 offset:924
	s_waitcnt lgkmcnt(0)
	v_cvt_pk_bf16_f32 v96, v112, v113
	v_cvt_pk_bf16_f32 v97, v114, v115
	v_cvt_pk_bf16_f32 v98, v116, v117
	v_cvt_pk_bf16_f32 v99, v118, v119
	global_store_dwordx4 v9, v[96:99], s[20:21] nt
	s_add_u32 s20, s20, s19
	s_addc_u32 s21, s21, 0
	ds_read_b32 v120, v7 offset:32
	ds_read_b32 v121, v7 offset:164
	ds_read_b32 v122, v7 offset:296
	ds_read_b32 v123, v7 offset:428
	ds_read_b32 v124, v7 offset:560
	ds_read_b32 v125, v7 offset:692
	ds_read_b32 v126, v7 offset:824
	ds_read_b32 v127, v7 offset:956
	s_waitcnt lgkmcnt(0)
	v_cvt_pk_bf16_f32 v100, v120, v121
	v_cvt_pk_bf16_f32 v101, v122, v123
	v_cvt_pk_bf16_f32 v102, v124, v125
	v_cvt_pk_bf16_f32 v103, v126, v127
	global_store_dwordx4 v9, v[100:103], s[20:21] nt
	s_add_u32 s20, s20, s19
	s_addc_u32 s21, s21, 0
	ds_read_b32 v128, v7 offset:64
	ds_read_b32 v129, v7 offset:196
	ds_read_b32 v130, v7 offset:328
	ds_read_b32 v131, v7 offset:460
	ds_read_b32 v132, v7 offset:592
	ds_read_b32 v133, v7 offset:724
	ds_read_b32 v134, v7 offset:856
	ds_read_b32 v135, v7 offset:988
	s_waitcnt lgkmcnt(0)
	v_cvt_pk_bf16_f32 v104, v128, v129
	v_cvt_pk_bf16_f32 v105, v130, v131
	v_cvt_pk_bf16_f32 v106, v132, v133
	v_cvt_pk_bf16_f32 v107, v134, v135
	global_store_dwordx4 v9, v[104:107], s[20:21] nt
	s_add_u32 s20, s20, s19
	s_addc_u32 s21, s21, 0
	ds_read_b32 v136, v7 offset:96
	ds_read_b32 v137, v7 offset:228
	ds_read_b32 v138, v7 offset:360
	ds_read_b32 v139, v7 offset:492
	ds_read_b32 v140, v7 offset:624
	ds_read_b32 v141, v7 offset:756
	ds_read_b32 v142, v7 offset:888
	ds_read_b32 v143, v7 offset:1020
	s_waitcnt lgkmcnt(0)
	v_cvt_pk_bf16_f32 v108, v136, v137
	v_cvt_pk_bf16_f32 v109, v138, v139
	v_cvt_pk_bf16_f32 v110, v140, v141
	v_cvt_pk_bf16_f32 v111, v142, v143
	global_store_dwordx4 v9, v[108:111], s[20:21] nt
	v_mul_lo_u32 v9, v6, s13
	v_lshl_add_u32 v96, v5, 3, v9
	v_lshlrev_b32_e32 v9, 1, v96
	s_lshl_b32 s19, s13, 4
	ds_read_b32 v112, v7 offset:8448
	ds_read_b32 v113, v7 offset:8580
	ds_read_b32 v114, v7 offset:8712
	ds_read_b32 v115, v7 offset:8844
	ds_read_b32 v116, v7 offset:8976
	ds_read_b32 v117, v7 offset:9108
	ds_read_b32 v118, v7 offset:9240
	ds_read_b32 v119, v7 offset:9372
	s_waitcnt lgkmcnt(0)
	v_cvt_pk_bf16_f32 v96, v112, v113
	v_cvt_pk_bf16_f32 v97, v114, v115
	v_cvt_pk_bf16_f32 v98, v116, v117
	v_cvt_pk_bf16_f32 v99, v118, v119
	global_store_dwordx4 v9, v[96:99], s[14:15] nt
	s_add_u32 s14, s14, s19
	s_addc_u32 s15, s15, 0
	ds_read_b32 v120, v7 offset:8480
	ds_read_b32 v121, v7 offset:8612
	ds_read_b32 v122, v7 offset:8744
	ds_read_b32 v123, v7 offset:8876
	ds_read_b32 v124, v7 offset:9008
	ds_read_b32 v125, v7 offset:9140
	ds_read_b32 v126, v7 offset:9272
	ds_read_b32 v127, v7 offset:9404
	s_waitcnt lgkmcnt(0)
	v_cvt_pk_bf16_f32 v100, v120, v121
	v_cvt_pk_bf16_f32 v101, v122, v123
	v_cvt_pk_bf16_f32 v102, v124, v125
	v_cvt_pk_bf16_f32 v103, v126, v127
	global_store_dwordx4 v9, v[100:103], s[14:15] nt
	s_add_u32 s14, s14, s19
	s_addc_u32 s15, s15, 0
	ds_read_b32 v128, v7 offset:8512
	ds_read_b32 v129, v7 offset:8644
	ds_read_b32 v130, v7 offset:8776
	ds_read_b32 v131, v7 offset:8908
	ds_read_b32 v132, v7 offset:9040
	ds_read_b32 v133, v7 offset:9172
	ds_read_b32 v134, v7 offset:9304
	ds_read_b32 v135, v7 offset:9436
	s_waitcnt lgkmcnt(0)
	v_cvt_pk_bf16_f32 v104, v128, v129
	v_cvt_pk_bf16_f32 v105, v130, v131
	v_cvt_pk_bf16_f32 v106, v132, v133
	v_cvt_pk_bf16_f32 v107, v134, v135
	global_store_dwordx4 v9, v[104:107], s[14:15] nt
	s_add_u32 s14, s14, s19
	s_addc_u32 s15, s15, 0
	ds_read_b32 v136, v7 offset:8544
	ds_read_b32 v137, v7 offset:8676
	ds_read_b32 v138, v7 offset:8808
	ds_read_b32 v139, v7 offset:8940
	ds_read_b32 v140, v7 offset:9072
	ds_read_b32 v141, v7 offset:9204
	ds_read_b32 v142, v7 offset:9336
	ds_read_b32 v143, v7 offset:9468
	s_waitcnt lgkmcnt(0)
	v_cvt_pk_bf16_f32 v108, v136, v137
	v_cvt_pk_bf16_f32 v109, v138, v139
	v_cvt_pk_bf16_f32 v110, v140, v141
	v_cvt_pk_bf16_f32 v111, v142, v143
	global_store_dwordx4 v9, v[108:111], s[14:15] nt
	s_add_i32 s6, s23, s7
	s_cmpk_lt_u32 s6, 4736
	s_cbranch_scc1 .Lcv3_item
	s_branch .Lcv3_end

.Lcv3_go_s:
	s_mul_i32 s1, s17, s12
	s_add_i32 s1, s1, s18
	s_lshl_b32 s1, s1, 2
	s_add_u32 s10, s10, s1
	s_addc_u32 s11, s11, 0
	v_mul_lo_u32 v8, v3, s12
	v_add_lshl_u32 v8, v8, v2, 2
	s_lshl_b32 s19, s12, 3
	global_load_dword v16, v8, s[10:11] nt
	s_add_u32 s10, s10, s19
	s_addc_u32 s11, s11, 0
	global_load_dword v17, v8, s[10:11] nt
	s_add_u32 s10, s10, s19
	s_addc_u32 s11, s11, 0
	global_load_dword v18, v8, s[10:11] nt
	s_add_u32 s10, s10, s19
	s_addc_u32 s11, s11, 0
	global_load_dword v19, v8, s[10:11] nt
	s_add_u32 s10, s10, s19
	s_addc_u32 s11, s11, 0
	global_load_dword v20, v8, s[10:11] nt
	s_add_u32 s10, s10, s19
	s_addc_u32 s11, s11, 0
	global_load_dword v21, v8, s[10:11] nt
	s_add_u32 s10, s10, s19
	s_addc_u32 s11, s11, 0
	global_load_dword v22, v8, s[10:11] nt
	s_add_u32 s10, s10, s19
	s_addc_u32 s11, s11, 0
	global_load_dword v23, v8, s[10:11] nt
	s_add_u32 s10, s10, s19
	s_addc_u32 s11, s11, 0
	global_load_dword v24, v8, s[10:11] nt
	s_add_u32 s10, s10, s19
	s_addc_u32 s11, s11, 0
	global_load_dword v25, v8, s[10:11] nt
	s_add_u32 s10, s10, s19
	s_addc_u32 s11, s11, 0
	global_load_dword v26, v8, s[10:11] nt
	s_add_u32 s10, s10, s19
	s_addc_u32 s11, s11, 0
	global_load_dword v27, v8, s[10:11] nt
	s_add_u32 s10, s10, s19
	s_addc_u32 s11, s11, 0
	global_load_dword v28, v8, s[10:11] nt
	s_add_u32 s10, s10, s19
	s_addc_u32 s11, s11, 0
	global_load_dword v29, v8, s[10:11] nt
	s_add_u32 s10, s10, s19
	s_addc_u32 s11, s11, 0
	global_load_dword v30, v8, s[10:11] nt
	s_add_u32 s10, s10, s19
	s_addc_u32 s11, s11, 0
	global_load_dword v31, v8, s[10:11] nt
	s_add_u32 s10, s10, s19
	s_addc_u32 s11, s11, 0
	global_load_dword v32, v8, s[10:11] nt
	s_add_u32 s10, s10, s19
	s_addc_u32 s11, s11, 0
	global_load_dword v33, v8, s[10:11] nt
	s_add_u32 s10, s10, s19
	s_addc_u32 s11, s11, 0
	global_load_dword v34, v8, s[10:11] nt
	s_add_u32 s10, s10, s19
	s_addc_u32 s11, s11, 0
	global_load_dword v35, v8, s[10:11] nt
	s_add_u32 s10, s10, s19
	s_addc_u32 s11, s11, 0
	global_load_dword v36, v8, s[10:11] nt
	s_add_u32 s10, s10, s19
	s_addc_u32 s11, s11, 0
	global_load_dword v37, v8, s[10:11] nt
	s_add_u32 s10, s10, s19
	s_addc_u32 s11, s11, 0
	global_load_dword v38, v8, s[10:11] nt
	s_add_u32 s10, s10, s19
	s_addc_u32 s11, s11, 0
	global_load_dword v39, v8, s[10:11] nt
	s_add_u32 s10, s10, s19
	s_addc_u32 s11, s11, 0
	global_load_dword v40, v8, s[10:11] nt
	s_add_u32 s10, s10, s19
	s_addc_u32 s11, s11, 0
	global_load_dword v41, v8, s[10:11] nt
	s_add_u32 s10, s10, s19
	s_addc_u32 s11, s11, 0
	global_load_dword v42, v8, s[10:11] nt
	s_add_u32 s10, s10, s19
	s_addc_u32 s11, s11, 0
	global_load_dword v43, v8, s[10:11] nt
	s_add_u32 s10, s10, s19
	s_addc_u32 s11, s11, 0
	global_load_dword v44, v8, s[10:11] nt
	s_add_u32 s10, s10, s19
	s_addc_u32 s11, s11, 0
	global_load_dword v45, v8, s[10:11] nt
	s_add_u32 s10, s10, s19
	s_addc_u32 s11, s11, 0
	global_load_dword v46, v8, s[10:11] nt
	s_add_u32 s10, s10, s19
	s_addc_u32 s11, s11, 0
	global_load_dword v47, v8, s[10:11] nt
	s_mul_i32 s1, s16, s13
	s_add_i32 s1, s1, s17
	s_lshl_b32 s1, s1, 1
	s_add_u32 s14, s14, s1
	s_addc_u32 s15, s15, 0
	s_waitcnt vmcnt(31)
	ds_write_b32 v4, v16 offset:0
	s_waitcnt vmcnt(30)
	ds_write_b32 v4, v17 offset:264
	s_waitcnt vmcnt(29)
	ds_write_b32 v4, v18 offset:528
	s_waitcnt vmcnt(28)
	ds_write_b32 v4, v19 offset:792
	s_waitcnt vmcnt(27)
	ds_write_b32 v4, v20 offset:1056
	s_waitcnt vmcnt(26)
	ds_write_b32 v4, v21 offset:1320
	s_waitcnt vmcnt(25)
	ds_write_b32 v4, v22 offset:1584
	s_waitcnt vmcnt(24)
	ds_write_b32 v4, v23 offset:1848
	s_waitcnt vmcnt(23)
	ds_write_b32 v4, v24 offset:2112
	s_waitcnt vmcnt(22)
	ds_write_b32 v4, v25 offset:2376
	s_waitcnt vmcnt(21)
	ds_write_b32 v4, v26 offset:2640
	s_waitcnt vmcnt(20)
	ds_write_b32 v4, v27 offset:2904
	s_waitcnt vmcnt(19)
	ds_write_b32 v4, v28 offset:3168
	s_waitcnt vmcnt(18)
	ds_write_b32 v4, v29 offset:3432
	s_waitcnt vmcnt(17)
	ds_write_b32 v4, v30 offset:3696
	s_waitcnt vmcnt(16)
	ds_write_b32 v4, v31 offset:3960
	s_waitcnt vmcnt(15)
	ds_write_b32 v4, v32 offset:4224
	s_waitcnt vmcnt(14)
	ds_write_b32 v4, v33 offset:4488
	s_waitcnt vmcnt(13)
	ds_write_b32 v4, v34 offset:4752
	s_waitcnt vmcnt(12)
	ds_write_b32 v4, v35 offset:5016
	s_waitcnt vmcnt(11)
	ds_write_b32 v4, v36 offset:5280
	s_waitcnt vmcnt(10)
	ds_write_b32 v4, v37 offset:5544
	s_waitcnt vmcnt(9)
	ds_write_b32 v4, v38 offset:5808
	s_waitcnt vmcnt(8)
	ds_write_b32 v4, v39 offset:6072
	s_waitcnt vmcnt(7)
	ds_write_b32 v4, v40 offset:6336
	s_waitcnt vmcnt(6)
	ds_write_b32 v4, v41 offset:6600
	s_waitcnt vmcnt(5)
	ds_write_b32 v4, v42 offset:6864
	s_waitcnt vmcnt(4)
	ds_write_b32 v4, v43 offset:7128
	s_waitcnt vmcnt(3)
	ds_write_b32 v4, v44 offset:7392
	s_waitcnt vmcnt(2)
	ds_write_b32 v4, v45 offset:7656
	s_waitcnt vmcnt(1)
	ds_write_b32 v4, v46 offset:7920
	s_waitcnt vmcnt(0)
	ds_write_b32 v4, v47 offset:8184
	s_waitcnt lgkmcnt(0)
	v_mul_lo_u32 v9, v6, s13
	v_lshl_add_u32 v96, v5, 3, v9
	v_lshlrev_b32_e32 v9, 1, v96
	s_lshl_b32 s19, s13, 4
	ds_read_b32 v112, v7 offset:0
	ds_read_b32 v113, v7 offset:132
	ds_read_b32 v114, v7 offset:264
	ds_read_b32 v115, v7 offset:396
	ds_read_b32 v116, v7 offset:528
	ds_read_b32 v117, v7 offset:660
	ds_read_b32 v118, v7 offset:792
	ds_read_b32 v119, v7 offset:924
	s_waitcnt lgkmcnt(0)
	v_cvt_pk_bf16_f32 v96, v112, v113
	v_cvt_pk_bf16_f32 v97, v114, v115
	v_cvt_pk_bf16_f32 v98, v116, v117
	v_cvt_pk_bf16_f32 v99, v118, v119
	global_store_dwordx4 v9, v[96:99], s[14:15] nt
	s_add_u32 s14, s14, s19
	s_addc_u32 s15, s15, 0
	ds_read_b32 v120, v7 offset:32
	ds_read_b32 v121, v7 offset:164
	ds_read_b32 v122, v7 offset:296
	ds_read_b32 v123, v7 offset:428
	ds_read_b32 v124, v7 offset:560
	ds_read_b32 v125, v7 offset:692
	ds_read_b32 v126, v7 offset:824
	ds_read_b32 v127, v7 offset:956
	s_waitcnt lgkmcnt(0)
	v_cvt_pk_bf16_f32 v100, v120, v121
	v_cvt_pk_bf16_f32 v101, v122, v123
	v_cvt_pk_bf16_f32 v102, v124, v125
	v_cvt_pk_bf16_f32 v103, v126, v127
	global_store_dwordx4 v9, v[100:103], s[14:15] nt
	s_add_u32 s14, s14, s19
	s_addc_u32 s15, s15, 0
	ds_read_b32 v128, v7 offset:64
	ds_read_b32 v129, v7 offset:196
	ds_read_b32 v130, v7 offset:328
	ds_read_b32 v131, v7 offset:460
	ds_read_b32 v132, v7 offset:592
	ds_read_b32 v133, v7 offset:724
	ds_read_b32 v134, v7 offset:856
	ds_read_b32 v135, v7 offset:988
	s_waitcnt lgkmcnt(0)
	v_cvt_pk_bf16_f32 v104, v128, v129
	v_cvt_pk_bf16_f32 v105, v130, v131
	v_cvt_pk_bf16_f32 v106, v132, v133
	v_cvt_pk_bf16_f32 v107, v134, v135
	global_store_dwordx4 v9, v[104:107], s[14:15] nt
	s_add_u32 s14, s14, s19
	s_addc_u32 s15, s15, 0
	ds_read_b32 v136, v7 offset:96
	ds_read_b32 v137, v7 offset:228
	ds_read_b32 v138, v7 offset:360
	ds_read_b32 v139, v7 offset:492
	ds_read_b32 v140, v7 offset:624
	ds_read_b32 v141, v7 offset:756
	ds_read_b32 v142, v7 offset:888
	ds_read_b32 v143, v7 offset:1020
	s_waitcnt lgkmcnt(0)
	v_cvt_pk_bf16_f32 v108, v136, v137
	v_cvt_pk_bf16_f32 v109, v138, v139
	v_cvt_pk_bf16_f32 v110, v140, v141
	v_cvt_pk_bf16_f32 v111, v142, v143
	global_store_dwordx4 v9, v[108:111], s[14:15] nt
.Lcv3_end:
.LBB0_796:
	s_cmp_lt_i32 s91, 6
	s_cbranch_scc1 .LBB0_850
	s_waitcnt vmcnt(0)
	s_waitcnt vmcnt(0) lgkmcnt(0)
	s_barrier
	s_mov_b64 s[0:1], exec
	v_readlane_b32 s2, v255, 5
	v_readlane_b32 s3, v255, 6
	s_and_b64 s[2:3], s[0:1], s[2:3]
	s_mov_b64 exec, s[2:3]
	s_cbranch_execz .LBB0_849
	s_add_u32 s2, s26, 0x4200
	s_addc_u32 s3, s27, 0
	s_add_i32 s4, 0, 0x24160
	v_mov_b32_e32 v1, s4
	s_waitcnt vmcnt(0) expcnt(0) lgkmcnt(0)
	ds_read_b32 v3, v1
	s_add_i32 s4, 0, 0x24164
	v_mov_b32_e32 v1, s4
	ds_read_b32 v1, v1
	s_waitcnt lgkmcnt(1)
	v_cmp_ne_u32_e32 vcc, 0, v3
	s_cbranch_vccnz .LBB0_813
	s_add_u32 s4, s26, 0x4400
	s_addc_u32 s5, s27, 0
	s_add_u32 s6, s26, 0x4500
	s_addc_u32 s7, s27, 0
	s_add_u32 s8, s26, 0x4600
	s_addc_u32 s9, s27, 0
	s_add_u32 s10, s26, 0x4700
	s_addc_u32 s11, s27, 0
	s_add_u32 s12, s26, 0x4800
	s_addc_u32 s13, s27, 0
	s_add_u32 s14, s26, 0x4900
	s_addc_u32 s15, s27, 0
	s_add_u32 s16, s26, 0x4a00
	s_addc_u32 s17, s27, 0
	s_add_u32 s18, s26, 0x4b00
	s_addc_u32 s19, s27, 0
	s_add_u32 s20, s26, 0x4c00
	s_addc_u32 s21, s27, 0
	s_add_u32 s22, s26, 0x4d00
	s_addc_u32 s23, s27, 0
	s_add_u32 s30, s26, 0x4e00
	s_addc_u32 s31, s27, 0
	s_add_u32 s34, s26, 0x4f00
	s_addc_u32 s35, s27, 0
	v_readlane_b32 s40, v255, 0
	s_add_u32 s36, s26, 0x5000
	v_readlane_b32 s41, v255, 1
	s_addc_u32 s37, s27, 0
	s_load_dwordx2 s[28:29], s[40:41], 0x4
	s_add_u32 s38, s26, 0x5100
	s_addc_u32 s39, s27, 0
	s_add_u32 s40, s26, 0x5200
	s_addc_u32 s41, s27, 0
	s_add_u32 s42, s26, 0x5300
	s_waitcnt lgkmcnt(0)
	s_mul_i32 s25, s28, s33
	s_addc_u32 s43, s27, 0
	s_mul_i32 s25, s25, s29
	s_mov_b32 s28, 1
	v_mov_b32_e32 v17, 0
	s_branch .LBB0_801
